# XCD-local barrier: this CU's L1 invalidate issued at arrival (all waves parked, no L1 fills until release) instead of after the release is observed
# baseline (speedup 1.0000x reference)
.LBB0_566:
	v_readlane_b32 s8, v232, 13
	v_readlane_b32 s9, v232, 14
	s_and_b64 vcc, exec, s[8:9]
	s_cbranch_vccz .LBB0_586
	s_waitcnt vmcnt(0)
	s_waitcnt vmcnt(0) lgkmcnt(0)
	s_barrier
	s_and_saveexec_b64 s[0:1], s[86:87]
	s_cbranch_execz .LBB0_585
	buffer_inv sc1
	s_mov_b64 s[34:35], exec
	v_mbcnt_lo_u32_b32 v0, s34, 0
	v_mbcnt_hi_u32_b32 v0, s35, v0
	v_cmp_eq_u32_e32 vcc, 0, v0
	s_and_saveexec_b64 s[8:9], vcc
	s_cbranch_execz .LBB0_570
	s_bcnt1_i32_b64 s34, s[34:35]
	v_mov_b32_e32 v1, s34
	v_readlane_b32 s34, v234, 34
	v_readlane_b32 s35, v234, 35
	s_nop 4
	global_atomic_add v1, v97, v1, s[34:35] sc0

.LBB0_584:
	s_or_b64 exec, exec, s[8:9]
	s_waitcnt vmcnt(0)
	s_waitcnt vmcnt(0)
